# FoX/DSA attention loops: v_pk_fma_f32 (scale+bias before exp) split into scalar v_fma_f32 pairs (bit-identical)
# speedup vs baseline: 1.0024x; 1.0024x over previous
; #define SBAR() do { asm volatile("s_waitcnt vmcnt(0) lgkmcnt(0)" ::: "memory"); __syncthreads(); } while (0)
; #define SBAR() __builtin_amdgcn_sched_barrier(0)
; #define VMW() asm volatile("s_waitcnt vmcnt(0)" ::: "memory")
; #define SLOAD_H(Kp, Vp, k0) do { S.st_v0 = LD8(ROW(Vp, k0, sr)); S.st_v1 = LD8(ROW(Vp, k0, 32 + sr));              \
;                          S.st_k0 = LD8(ROW(Kp, k0, sr)); S.st_k1 = LD8(ROW(Kp, k0, 32 + sr)); } while (0)
; #define SWRITE_HV(bf) do { *(bf16x8*)(V_lds + (bf) * SHM_V + vst0) = S.st_v0; *(bf16x8*)(V_lds + (bf) * SHM_V + vst1) = S.st_v1; } while (0)
; #define SWRITE_H(bf) do { SWRITE_HV(bf); SWRITE_HK(bf); } while (0)
; #define MLOAD(t) MLOAD_(t, moff)
; __device__ __forceinline__ void partialSM(f32x16& p0, f32x16& p1, float& m_reg, float& mn, float& alpha) {
;     float pmax = p0[0];
; #pragma unroll
;     for (int r = 1; r < 16; ++r) pmax = fmaxf(pmax, p0[r]);
; #pragma unroll
;     for (int r = 0; r < 16; ++r) pmax = fmaxf(pmax, p1[r]);
;     { auto rr = __builtin_amdgcn_permlane32_swap(__float_as_uint(pmax), __float_as_uint(pmax), false, false);
;       pmax = fmaxf(__uint_as_float(rr[0]), __uint_as_float(rr[1])); }
;     constexpr float C2 = 1.4426950408889634f * SM_SCALE;
;     if (__builtin_expect(__all((pmax - m_reg) * SM_SCALE <= THR), 1)) { mn = m_reg; alpha = 1.f; }
;     else { mn = fmaxf(m_reg, pmax); alpha = __builtin_amdgcn_exp2f((m_reg - mn) * C2); m_reg = mn; }
;     const float mnL = -mn * C2;
; #pragma unroll
;     for (int r = 0; r < 16; ++r) p0[r] = fmaf(p0[r], C2, mnL);
; #pragma unroll
;     for (int r = 0; r < 16; ++r) p1[r] = fmaf(p1[r], C2, mnL);
; #pragma unroll
;     for (int r = 0; r < 16; ++r) p0[r] = __builtin_amdgcn_exp2f(p0[r]);
; template <int MODE>
; __device__ __forceinline__ void block(const Ref& cur, const Ref& nxt, char* lds, Seam& S) {
;     ...
;     BLOAD(bz0, bz1, 0);
;     SWRITE_HV(0); SBAR();
;     if (NT > 1) SLOAD_H(Kh, Vh, KBASE(1));
;     MLOAD(0);
;     SBAR(); qkt<0, MODE>(pA0, pA1, K_lds, r32, hi, S.qr, bz0, bz1);
;     if (NT > 1) BLOAD(bz0, bz1, 1);
;     MASKT(pA0, pA1, 0); partialSM(pA0, pA1, m_reg, mnA, alA);
;     if (NT > 1) { VMW(); SWRITE_H(1); }
;     __syncthreads();
;     ...
;     for (int t = 1; t + 1 < NT; t += 2) {
;         HALF_STEP(pB0, pB1, mnB, alB, pA0, pA1, alA, t, 1, 0, 0);
;         HALF_STEP(pA0, pA1, mnA, alA, pB0, pB1, alB, t + 1, 0, 1, 1);
;     }
.LBB0_538:
	v_max_f32_e32 v3, 0xf149f2ca, v2
	v_cndmask_b32_e64 v182, v3, v228, s[8:9]
	v_sub_f32_e32 v3, 0xf149f2ca, v3
	v_mul_f32_e32 v2, 0xbe0293ee, v182
	v_mul_f32_e32 v3, 0x3e0293ee, v3
	v_fmamk_f32 v5, v6, 0x3e0293ee, v2
	v_fmamk_f32 v6, v7, 0x3e0293ee, v2
	v_fmamk_f32 v7, v8, 0x3e0293ee, v2
	v_fmamk_f32 v8, v9, 0x3e0293ee, v2
	v_fmamk_f32 v9, v10, 0x3e0293ee, v2
	v_fmamk_f32 v10, v11, 0x3e0293ee, v2
	v_fmamk_f32 v11, v12, 0x3e0293ee, v2
	v_fmamk_f32 v12, v13, 0x3e0293ee, v2
	v_fmamk_f32 v13, v14, 0x3e0293ee, v2
	v_fmamk_f32 v14, v15, 0x3e0293ee, v2
	v_fmamk_f32 v15, v16, 0x3e0293ee, v2
	v_fmamk_f32 v16, v17, 0x3e0293ee, v2
	v_fmamk_f32 v17, v18, 0x3e0293ee, v2
	v_fmamk_f32 v18, v19, 0x3e0293ee, v2
	v_fmamk_f32 v19, v20, 0x3e0293ee, v2
	v_fmamk_f32 v20, v21, 0x3e0293ee, v2
	v_exp_f32_e32 v3, v3
	s_and_b32 s5, s5, 0x3fffffc0
	v_exp_f32_e32 v193, v5
	v_exp_f32_e32 v195, v6
	v_exp_f32_e32 v191, v7
	v_exp_f32_e32 v194, v8
	v_exp_f32_e32 v189, v9
	v_exp_f32_e32 v192, v10
	v_exp_f32_e32 v188, v11
	v_exp_f32_e32 v190, v12
	v_exp_f32_e32 v181, v13
	v_exp_f32_e32 v185, v14
	v_exp_f32_e32 v180, v15
	v_exp_f32_e32 v183, v16
	v_exp_f32_e32 v179, v17
	v_exp_f32_e32 v187, v18
	v_exp_f32_e32 v184, v19
	v_exp_f32_e32 v186, v20
	s_lshl_b32 s5, s5, 2
	s_add_i32 s75, s5, 0
	s_add_i32 s75, s75, 0x10000
	v_cndmask_b32_e64 v205, v3, 1.0, s[8:9]
	v_fma_f32 v130, v36, s82, v2
	v_fma_f32 v131, v37, s82, v2
	v_fma_f32 v132, v34, s82, v2
	v_fma_f32 v133, v35, s82, v2
	v_fma_f32 v134, v32, s82, v2
	v_fma_f32 v135, v33, s82, v2
	v_fma_f32 v136, v30, s82, v2
	v_fma_f32 v137, v31, s82, v2
	v_fma_f32 v138, v28, s82, v2
	v_fma_f32 v139, v29, s82, v2
	v_fma_f32 v140, v26, s82, v2
	v_fma_f32 v141, v27, s82, v2
	v_fma_f32 v142, v24, s82, v2
	v_fma_f32 v143, v25, s82, v2
	v_fma_f32 v144, v22, s82, v2
	v_fma_f32 v145, v23, s82, v2
	s_cmp_lt_i32 s97, 3
	s_waitcnt lgkmcnt(0)
	s_barrier
	s_cbranch_scc1 .LBB0_557
	v_mov_b32_e32 v39, v4
	v_add_u32_e32 v2, 0xffffff80, v225
	v_mov_b32_e32 v231, 0
	v_writelane_b32 v254, s33, 45
	s_mov_b32 s33, s72
	v_lshl_add_u64 v[206:207], s[78:79], 0, v[38:39]
	v_lshl_add_u64 v[208:209], s[76:77], 0, v[38:39]
	s_mov_b32 s5, 2
	v_lshl_add_u32 v232, v212, 2, s75
	v_lshl_add_u32 v233, v216, 2, s75
	v_add_u32_e32 v234, s74, v2
	s_movk_i32 s72, 0x7f
	v_mov_b32_e32 v66, 0
	v_mov_b32_e32 v67, v231
	v_mov_b32_e32 v68, v231
	v_mov_b32_e32 v69, v231
	v_mov_b32_e32 v70, v231
	v_mov_b32_e32 v71, v231
	v_mov_b32_e32 v72, v231
	v_mov_b32_e32 v73, v231
	v_mov_b32_e32 v74, v231
	v_mov_b32_e32 v75, v231
	v_mov_b32_e32 v76, v231
	v_mov_b32_e32 v77, v231
	v_mov_b32_e32 v78, v231
	v_mov_b32_e32 v79, v231
	v_mov_b32_e32 v80, v231
	v_mov_b32_e32 v81, v231
	v_mov_b32_e32 v50, 0
	v_mov_b32_e32 v51, v231
	v_mov_b32_e32 v52, v231
	v_mov_b32_e32 v53, v231
	v_mov_b32_e32 v54, v231
	v_mov_b32_e32 v55, v231
	v_mov_b32_e32 v56, v231
	v_mov_b32_e32 v57, v231
	v_mov_b32_e32 v58, v231
	v_mov_b32_e32 v59, v231
	v_mov_b32_e32 v60, v231
	v_mov_b32_e32 v61, v231
	v_mov_b32_e32 v62, v231
	v_mov_b32_e32 v63, v231
	v_mov_b32_e32 v64, v231
	v_mov_b32_e32 v65, v231
	v_mov_b32_e32 v34, 0
	v_mov_b32_e32 v35, v231
	v_mov_b32_e32 v36, v231
	v_mov_b32_e32 v37, v231
	v_mov_b32_e32 v38, v231
	v_mov_b32_e32 v39, v231
	v_mov_b32_e32 v40, v231
	v_mov_b32_e32 v41, v231
	v_mov_b32_e32 v42, v231
	v_mov_b32_e32 v43, v231
	v_mov_b32_e32 v44, v231
	v_mov_b32_e32 v45, v231
	v_mov_b32_e32 v46, v231
	v_mov_b32_e32 v47, v231
	v_mov_b32_e32 v48, v231
	v_mov_b32_e32 v49, v231
	v_mov_b32_e32 v18, 0
	v_mov_b32_e32 v19, v231
	v_mov_b32_e32 v20, v231
	v_mov_b32_e32 v21, v231
	v_mov_b32_e32 v22, v231
	v_mov_b32_e32 v23, v231
	v_mov_b32_e32 v24, v231
	v_mov_b32_e32 v25, v231
	v_mov_b32_e32 v26, v231
	v_mov_b32_e32 v27, v231
	v_mov_b32_e32 v28, v231
	v_mov_b32_e32 v29, v231
	v_mov_b32_e32 v30, v231
	v_mov_b32_e32 v31, v231
	v_mov_b32_e32 v32, v231
	v_mov_b32_e32 v33, v231
	s_branch .LBB0_542

; __device__ __forceinline__ void partialSM(f32x16& p0, f32x16& p1, float& m_reg, float& mn, float& alpha) {
;     ...
;     constexpr float C2 = 1.4426950408889634f * SM_SCALE;
;     if (__builtin_expect(__all((pmax - m_reg) * SM_SCALE <= THR), 1)) { mn = m_reg; alpha = 1.f; }
;     else { mn = fmaxf(m_reg, pmax); alpha = __builtin_amdgcn_exp2f((m_reg - mn) * C2); m_reg = mn; }
;     const float mnL = -mn * C2;
; #pragma unroll
;     for (int r = 0; r < 16; ++r) p0[r] = fmaf(p0[r], C2, mnL);
; #pragma unroll
;     for (int r = 0; r < 16; ++r) p1[r] = fmaf(p1[r], C2, mnL);
; #pragma unroll
;     for (int r = 0; r < 16; ++r) p0[r] = __builtin_amdgcn_exp2f(p0[r]);
; template <int MODE>
; __device__ __forceinline__ void block(const Ref& cur, const Ref& nxt, char* lds, Seam& S) {
;     ...
;     for (int t = 1; t + 1 < NT; t += 2) {
;         HALF_STEP(pB0, pB1, mnB, alB, pA0, pA1, alA, t, 1, 0, 0);
;         HALF_STEP(pA0, pA1, mnA, alA, pB0, pB1, alB, t + 1, 0, 1, 1);
;     }
.LBB0_541:
	v_cndmask_b32_e64 v182, v6, v238, s[6:7]
	v_mul_f32_e32 v6, 0xbe0293ee, v182
	s_waitcnt vmcnt(3)
	v_fmamk_f32 v17, v140, 0x3e0293ee, v6
	v_fmamk_f32 v140, v141, 0x3e0293ee, v6
	v_fmamk_f32 v141, v142, 0x3e0293ee, v6
	v_fmamk_f32 v142, v143, 0x3e0293ee, v6
	v_fmamk_f32 v143, v144, 0x3e0293ee, v6
	v_mov_b32_e32 v144, v6
	v_fmamk_f32 v7, v130, 0x3e0293ee, v6
	v_fmamk_f32 v8, v131, 0x3e0293ee, v6
	v_fmamk_f32 v9, v132, 0x3e0293ee, v6
	v_fmamk_f32 v10, v133, 0x3e0293ee, v6
	v_fmamk_f32 v11, v134, 0x3e0293ee, v6
	v_fmamk_f32 v12, v135, 0x3e0293ee, v6
	v_fmamk_f32 v13, v136, 0x3e0293ee, v6
	v_fmamk_f32 v14, v137, 0x3e0293ee, v6
	v_fmamk_f32 v15, v138, 0x3e0293ee, v6
	v_fmamk_f32 v16, v139, 0x3e0293ee, v6
	v_fmac_f32_e32 v144, 0x3e0293ee, v145
	v_exp_f32_e32 v193, v7
	v_exp_f32_e32 v195, v8
	v_exp_f32_e32 v191, v9
	v_exp_f32_e32 v194, v10
	v_exp_f32_e32 v189, v11
	v_exp_f32_e32 v192, v12
	v_exp_f32_e32 v188, v13
	v_exp_f32_e32 v190, v14
	s_waitcnt vmcnt(2)
	v_exp_f32_e32 v181, v15
	v_exp_f32_e32 v185, v16
	v_exp_f32_e32 v180, v17
	v_exp_f32_e32 v183, v140
	v_exp_f32_e32 v179, v141
	v_exp_f32_e32 v187, v142
	v_exp_f32_e32 v184, v143
	v_exp_f32_e32 v186, v144
	v_fma_f32 v130, v128, s82, v6
	v_fma_f32 v131, v129, s82, v6
	v_fma_f32 v132, v126, s82, v6
	v_fma_f32 v133, v127, s82, v6
	v_fma_f32 v134, v124, s82, v6
	v_fma_f32 v135, v125, s82, v6
	v_fma_f32 v136, v122, s82, v6
	v_fma_f32 v137, v123, s82, v6
	v_fma_f32 v138, v120, s82, v6
	v_fma_f32 v139, v121, s82, v6
	v_fma_f32 v140, v118, s82, v6
	v_fma_f32 v141, v119, s82, v6
	v_fma_f32 v142, v116, s82, v6
	v_fma_f32 v143, v117, s82, v6
	v_fma_f32 v144, v114, s82, v6
	v_fma_f32 v145, v115, s82, v6
	v_add_f32_e32 v6, v235, v236
	v_fmac_f32_e32 v6, v205, v231
	v_add_f32_e32 v231, v2, v3
	s_addk_i32 s72, 0x80
	s_add_i32 s5, s5, 2
	v_fmac_f32_e32 v231, v6, v237
	s_cmp_ge_i32 s5, s97
	v_add_u32_e32 v234, 0xffffff80, v234
	v_mov_b32_e32 v205, v5
	s_waitcnt lgkmcnt(0)
	s_barrier
	s_cbranch_scc1 .LBB0_558

; #define SBAR() do { asm volatile("s_waitcnt vmcnt(0) lgkmcnt(0)" ::: "memory"); __syncthreads(); } while (0)
; #define SBAR() __builtin_amdgcn_sched_barrier(0)
; #define VMW() asm volatile("s_waitcnt vmcnt(0)" ::: "memory")
; #define SLOAD_H(Kp, Vp, k0) do { S.st_v0 = LD8(ROW(Vp, k0, sr)); S.st_v1 = LD8(ROW(Vp, k0, 32 + sr));              \
;                          S.st_k0 = LD8(ROW(Kp, k0, sr)); S.st_k1 = LD8(ROW(Kp, k0, 32 + sr)); } while (0)
; #define SWRITE_HV(bf) do { *(bf16x8*)(V_lds + (bf) * SHM_V + vst0) = S.st_v0; *(bf16x8*)(V_lds + (bf) * SHM_V + vst1) = S.st_v1; } while (0)
; #define SWRITE_H(bf) do { SWRITE_HV(bf); SWRITE_HK(bf); } while (0)
; #define MLOAD(t) MLOAD_(t, moff)
; __device__ __forceinline__ void partialSM(f32x16& p0, f32x16& p1, float& m_reg, float& mn, float& alpha) {
;     float pmax = p0[0];
; #pragma unroll
;     for (int r = 1; r < 16; ++r) pmax = fmaxf(pmax, p0[r]);
; #pragma unroll
;     for (int r = 0; r < 16; ++r) pmax = fmaxf(pmax, p1[r]);
;     { auto rr = __builtin_amdgcn_permlane32_swap(__float_as_uint(pmax), __float_as_uint(pmax), false, false);
;       pmax = fmaxf(__uint_as_float(rr[0]), __uint_as_float(rr[1])); }
;     constexpr float C2 = 1.4426950408889634f * SM_SCALE;
;     if (__builtin_expect(__all((pmax - m_reg) * SM_SCALE <= THR), 1)) { mn = m_reg; alpha = 1.f; }
;     else { mn = fmaxf(m_reg, pmax); alpha = __builtin_amdgcn_exp2f((m_reg - mn) * C2); m_reg = mn; }
;     const float mnL = -mn * C2;
; #pragma unroll
;     for (int r = 0; r < 16; ++r) p0[r] = fmaf(p0[r], C2, mnL);
; #pragma unroll
;     for (int r = 0; r < 16; ++r) p1[r] = fmaf(p1[r], C2, mnL);
; #pragma unroll
;     for (int r = 0; r < 16; ++r) p0[r] = __builtin_amdgcn_exp2f(p0[r]);
; template <int MODE>
; __device__ __forceinline__ void block(const Ref& cur, const Ref& nxt, char* lds, Seam& S) {
;     ...
;     BLOAD(bz0, bz1, 0);
;     SWRITE_HV(0); SBAR();
;     if (NT > 1) SLOAD_H(Kh, Vh, KBASE(1));
;     MLOAD(0);
;     SBAR(); qkt<0, MODE>(pA0, pA1, K_lds, r32, hi, S.qr, bz0, bz1);
;     if (NT > 1) BLOAD(bz0, bz1, 1);
;     MASKT(pA0, pA1, 0); partialSM(pA0, pA1, m_reg, mnA, alA);
;     if (NT > 1) { VMW(); SWRITE_H(1); }
;     __syncthreads();
;     ...
;     for (int t = 1; t + 1 < NT; t += 2) {
;         HALF_STEP(pB0, pB1, mnB, alB, pA0, pA1, alA, t, 1, 0, 0);
;         HALF_STEP(pA0, pA1, mnA, alA, pB0, pB1, alB, t + 1, 0, 1, 1);
;     }
.LBB0_1224:
	v_mul_f32_e32 v36, 0xbe0293ee, v201
	v_mov_b32_e32 v35, v36
	v_fmamk_f32 v1, v1, 0x3e0293ee, v36
	v_fmamk_f32 v20, v20, 0x3e0293ee, v36
	v_fmamk_f32 v21, v21, 0x3e0293ee, v36
	v_fmamk_f32 v22, v22, 0x3e0293ee, v36
	v_fmamk_f32 v23, v23, 0x3e0293ee, v36
	v_fmamk_f32 v24, v24, 0x3e0293ee, v36
	v_fmamk_f32 v25, v25, 0x3e0293ee, v36
	v_fmamk_f32 v26, v26, 0x3e0293ee, v36
	v_fmamk_f32 v27, v27, 0x3e0293ee, v36
	v_fmamk_f32 v28, v28, 0x3e0293ee, v36
	v_fmamk_f32 v29, v29, 0x3e0293ee, v36
	v_fmamk_f32 v30, v30, 0x3e0293ee, v36
	v_fmamk_f32 v31, v31, 0x3e0293ee, v36
	v_fmamk_f32 v32, v32, 0x3e0293ee, v36
	v_fmamk_f32 v33, v33, 0x3e0293ee, v36
	v_fmac_f32_e32 v35, 0x3e0293ee, v34
	s_and_b32 s21, s21, 0x3fffffc0
	v_exp_f32_e32 v128, v1
	v_exp_f32_e32 v1, v20
	v_exp_f32_e32 v126, v21
	v_exp_f32_e32 v123, v22
	v_exp_f32_e32 v122, v23
	v_exp_f32_e32 v125, v24
	v_exp_f32_e32 v124, v25
	v_exp_f32_e32 v127, v26
	v_exp_f32_e32 v114, v27
	v_exp_f32_e32 v115, v28
	v_exp_f32_e32 v116, v29
	v_exp_f32_e32 v117, v30
	v_exp_f32_e32 v118, v31
	v_exp_f32_e32 v119, v32
	s_lshl_b32 s21, s21, 2
	v_exp_f32_e32 v120, v33
	v_exp_f32_e32 v121, v35
	s_add_i32 s28, s21, 0
	s_add_i32 s28, s28, 0x10000
	v_fma_f32 v178, v18, s8, v36
	v_fma_f32 v179, v19, s8, v36
	v_fma_f32 v180, v16, s8, v36
	v_fma_f32 v181, v17, s8, v36
	v_fma_f32 v182, v14, s8, v36
	v_fma_f32 v183, v15, s8, v36
	v_fma_f32 v184, v12, s8, v36
	v_fma_f32 v185, v13, s8, v36
	v_fma_f32 v186, v10, s8, v36
	v_fma_f32 v187, v11, s8, v36
	v_fma_f32 v188, v8, s8, v36
	v_fma_f32 v189, v9, s8, v36
	v_fma_f32 v190, v6, s8, v36
	v_fma_f32 v191, v7, s8, v36
	v_fma_f32 v192, v4, s8, v36
	v_fma_f32 v193, v5, s8, v36
	s_cmp_lt_i32 s20, 3
	s_waitcnt lgkmcnt(0)
	s_barrier
	s_cbranch_scc1 .LBB0_1243
	v_mov_b32_e32 v199, v3
	v_lshl_add_u64 v[16:17], s[26:27], 0, v[198:199]
	v_lshl_add_u64 v[206:207], s[24:25], 0, v[198:199]
	v_lshl_add_u64 v[4:5], s[22:23], 0, v[2:3]
	v_mov_b32_e32 v199, 0
	s_mov_b32 s21, 2
	v_lshl_add_u32 v226, v212, 2, s28
	v_lshl_add_u32 v227, v215, 2, s28
	v_lshl_add_u64 v[208:209], v[4:5], 0, 8
	v_mov_b32_e32 v2, v216
	v_mov_b32_e32 v66, 0
	v_mov_b32_e32 v67, v199
	v_mov_b32_e32 v68, v199
	v_mov_b32_e32 v69, v199
	v_mov_b32_e32 v70, v199
	v_mov_b32_e32 v71, v199
	v_mov_b32_e32 v72, v199
	v_mov_b32_e32 v73, v199
	v_mov_b32_e32 v74, v199
	v_mov_b32_e32 v75, v199
	v_mov_b32_e32 v76, v199
	v_mov_b32_e32 v77, v199
	v_mov_b32_e32 v78, v199
	v_mov_b32_e32 v79, v199
	v_mov_b32_e32 v80, v199
	v_mov_b32_e32 v81, v199
	v_mov_b32_e32 v50, 0
	v_mov_b32_e32 v51, v199
	v_mov_b32_e32 v52, v199
	v_mov_b32_e32 v53, v199
	v_mov_b32_e32 v54, v199
	v_mov_b32_e32 v55, v199
	v_mov_b32_e32 v56, v199
	v_mov_b32_e32 v57, v199
	v_mov_b32_e32 v58, v199
	v_mov_b32_e32 v59, v199
	v_mov_b32_e32 v60, v199
	v_mov_b32_e32 v61, v199
	v_mov_b32_e32 v62, v199
	v_mov_b32_e32 v63, v199
	v_mov_b32_e32 v64, v199
	v_mov_b32_e32 v65, v199
	v_mov_b32_e32 v34, 0
	v_mov_b32_e32 v35, v199
	v_mov_b32_e32 v36, v199
	v_mov_b32_e32 v37, v199
	v_mov_b32_e32 v38, v199
	v_mov_b32_e32 v39, v199
	v_mov_b32_e32 v40, v199
	v_mov_b32_e32 v41, v199
	v_mov_b32_e32 v42, v199
	v_mov_b32_e32 v43, v199
	v_mov_b32_e32 v44, v199
	v_mov_b32_e32 v45, v199
	v_mov_b32_e32 v46, v199
	v_mov_b32_e32 v47, v199
	v_mov_b32_e32 v48, v199
	v_mov_b32_e32 v49, v199
	v_mov_b32_e32 v18, 0
	v_mov_b32_e32 v19, v199
	v_mov_b32_e32 v20, v199
	v_mov_b32_e32 v21, v199
	v_mov_b32_e32 v22, v199
	v_mov_b32_e32 v23, v199
	v_mov_b32_e32 v24, v199
	v_mov_b32_e32 v25, v199
	v_mov_b32_e32 v26, v199
	v_mov_b32_e32 v27, v199
	v_mov_b32_e32 v28, v199
	v_mov_b32_e32 v29, v199
	v_mov_b32_e32 v30, v199
	v_mov_b32_e32 v31, v199
	v_mov_b32_e32 v32, v199
	v_mov_b32_e32 v33, v199
	s_branch .LBB0_1228

; __device__ __forceinline__ void partialSM(f32x16& p0, f32x16& p1, float& m_reg, float& mn, float& alpha) {
;     ...
;     constexpr float C2 = 1.4426950408889634f * SM_SCALE;
;     if (__builtin_expect(__all((pmax - m_reg) * SM_SCALE <= THR), 1)) { mn = m_reg; alpha = 1.f; }
;     else { mn = fmaxf(m_reg, pmax); alpha = __builtin_amdgcn_exp2f((m_reg - mn) * C2); m_reg = mn; }
;     const float mnL = -mn * C2;
; #pragma unroll
;     for (int r = 0; r < 16; ++r) p0[r] = fmaf(p0[r], C2, mnL);
; #pragma unroll
;     for (int r = 0; r < 16; ++r) p1[r] = fmaf(p1[r], C2, mnL);
; #pragma unroll
;     for (int r = 0; r < 16; ++r) p0[r] = __builtin_amdgcn_exp2f(p0[r]);
; template <int MODE>
; __device__ __forceinline__ void block(const Ref& cur, const Ref& nxt, char* lds, Seam& S) {
;     ...
;     for (int t = 1; t + 1 < NT; t += 2) {
;         HALF_STEP(pB0, pB1, mnB, alB, pA0, pA1, alA, t, 1, 0, 0);
;         HALF_STEP(pA0, pA1, mnA, alA, pB0, pB1, alB, t + 1, 0, 1, 1);
;     }
.LBB0_1227:
	v_fmamk_f32 v6, v133, 0x3e0293ee, v210
	v_mov_b32_e32 v133, v210
	v_fmamk_f32 v1, v1, 0x3e0293ee, v210
	v_fmamk_f32 v4, v131, 0x3e0293ee, v210
	v_fmamk_f32 v5, v132, 0x3e0293ee, v210
	v_fmamk_f32 v7, v134, 0x3e0293ee, v210
	v_fmamk_f32 v8, v135, 0x3e0293ee, v210
	v_fmamk_f32 v9, v136, 0x3e0293ee, v210
	v_fmamk_f32 v10, v137, 0x3e0293ee, v210
	v_fmamk_f32 v11, v138, 0x3e0293ee, v210
	v_fmamk_f32 v12, v139, 0x3e0293ee, v210
	v_fmamk_f32 v13, v140, 0x3e0293ee, v210
	v_fmamk_f32 v14, v141, 0x3e0293ee, v210
	v_fmamk_f32 v15, v142, 0x3e0293ee, v210
	v_fmamk_f32 v131, v143, 0x3e0293ee, v210
	v_fmamk_f32 v132, v144, 0x3e0293ee, v210
	v_fmac_f32_e32 v133, 0x3e0293ee, v145
	v_fma_f32 v178, v128, s8, v210
	v_fma_f32 v179, v129, s8, v210
	v_fma_f32 v180, v126, s8, v210
	v_fma_f32 v181, v127, s8, v210
	v_fma_f32 v182, v124, s8, v210
	v_fma_f32 v183, v125, s8, v210
	v_fma_f32 v184, v122, s8, v210
	v_fma_f32 v185, v123, s8, v210
	v_fma_f32 v186, v120, s8, v210
	v_fma_f32 v187, v121, s8, v210
	v_fma_f32 v188, v118, s8, v210
	v_fma_f32 v189, v119, s8, v210
	v_fma_f32 v190, v116, s8, v210
	v_fma_f32 v191, v117, s8, v210
	v_fma_f32 v192, v114, s8, v210
	v_fma_f32 v193, v115, s8, v210
	v_exp_f32_e32 v128, v1
	v_exp_f32_e32 v1, v4
	v_exp_f32_e32 v126, v5
	v_exp_f32_e32 v123, v6
	v_exp_f32_e32 v122, v7
	v_exp_f32_e32 v125, v8
	v_exp_f32_e32 v124, v9
	v_exp_f32_e32 v127, v10
	v_exp_f32_e32 v114, v11
	v_exp_f32_e32 v115, v12
	v_exp_f32_e32 v116, v13
	v_exp_f32_e32 v117, v14
	v_exp_f32_e32 v118, v15
	v_exp_f32_e32 v119, v131
	v_exp_f32_e32 v120, v132
	v_exp_f32_e32 v121, v133
	v_add_f32_e32 v4, v228, v229
	v_fmac_f32_e32 v4, v203, v199
	v_add_f32_e32 v199, v231, v232
	s_add_i32 s21, s21, 2
	v_fmac_f32_e32 v199, v4, v230
	v_lshl_add_u64 v[208:209], v[208:209], 0, 16
	s_cmp_ge_i32 s21, s20
	v_add_u32_e32 v2, 0x80, v2
	v_mov_b32_e32 v203, v130
	s_waitcnt lgkmcnt(0)
	s_barrier
	s_cbranch_scc1 .LBB0_1244
